# fused epilogues: residual-tile prefetch batch moved after the RMS-exchange arrival atomic so the publish wait no longer covers it
# baseline (speedup 1.0000x reference)
; __device__ __forceinline__ void panel_rms(const f32x4 (&v)[2][2][4][2], int pm, int pn, int wr, int wc, int fr, int fq, LAS unsigned char* xl, int wid, int lane, float* slots, unsigned* cnt) {
;     ...
;     asm volatile("s_waitcnt vmcnt(0)" ::: "memory");
;     if (lane == 0) __hip_atomic_fetch_add(cnt + 64 * pm, 1u, __ATOMIC_RELAXED, __HIP_MEMORY_SCOPE_AGENT);
;     if (wid == 0) {
;         unsigned sp = 0;
;         while ((unsigned)__builtin_amdgcn_readfirstlane((int)__hip_atomic_load(cnt + 64 * pm, __ATOMIC_RELAXED, __HIP_MEMORY_SCOPE_AGENT)) < 32u) { __builtin_amdgcn_s_sleep(2); if (++sp > (1u << 21)) break; }
; __device__ __forceinline__ void fused_epi(f32x4 (&acc)[2][2][4][2], const Unit& u, int wr, int wc, int fr, int fq, LAS unsigned char* xl, int wid, int lane, const FuseArgs& f) {
;     ...
;                 for (int bj = 0; bj < 2; ++bj) { const size_t off = (size_t)(pm * BM + r) * DM + colb + bj * HALF;
;                     const u32x4 xw = *(const u32x4*)((const bf16_t*)(f.ws + WS_XR) + off);
.LBB0_84:
	s_or_b64 exec, exec, s[12:13]
	s_lshl_b32 s32, s53, 19
	s_add_u32 s34, s78, s32
	s_addc_u32 s35, s79, 0
	s_lshl_b32 s32, s22, 9
	s_add_u32 s34, s34, s32
	s_addc_u32 s35, s35, 0
	v_lshlrev_b32_e32 v217, 11, v167
	v_lshl_add_u32 v217, v213, 1, v217
	global_load_dwordx4 v[224:227], v217, s[34:35]
	global_load_dwordx4 v[228:231], v217, s[34:35] offset:256
	v_lshlrev_b32_e32 v217, 11, v198
	v_lshl_add_u32 v217, v213, 1, v217
	global_load_dwordx4 v[232:235], v217, s[34:35]
	global_load_dwordx4 v[236:239], v217, s[34:35] offset:256
	v_lshlrev_b32_e32 v217, 11, v200
	v_lshl_add_u32 v217, v213, 1, v217
	global_load_dwordx4 v[240:243], v217, s[34:35]
	global_load_dwordx4 v[244:247], v217, s[34:35] offset:256
	v_lshlrev_b32_e32 v217, 11, v202
	v_lshl_add_u32 v217, v213, 1, v217
	global_load_dwordx4 v[248:251], v217, s[34:35]
	v_readlane_b32 s12, v255, 31
	v_readlane_b32 s13, v255, 32
	s_andn2_b64 vcc, exec, s[12:13]
	s_cbranch_vccnz .LBB0_98
	s_lshl_b32 s12, s53, 6
	s_ashr_i32 s13, s12, 31
	s_lshl_b64 s[12:13], s[12:13], 2
	s_add_u32 s12, s39, s12
	s_addc_u32 s13, s47, s13
	s_mov_b32 s21, 0x200001
	s_branch .LBB0_87

; __device__ __forceinline__ void panel_rms(const f32x4 (&v)[2][2][4][2], int pm, int pn, int wr, int wc, int fr, int fq, LAS unsigned char* xl, int wid, int lane, float* slots, unsigned* cnt) {
;     ...
;     asm volatile("s_waitcnt vmcnt(0)" ::: "memory");
;     if (lane == 0) __hip_atomic_fetch_add(cnt + 64 * pm, 1u, __ATOMIC_RELAXED, __HIP_MEMORY_SCOPE_AGENT);
;     if (wid == 0) {
;         unsigned sp = 0;
;         while ((unsigned)__builtin_amdgcn_readfirstlane((int)__hip_atomic_load(cnt + 64 * pm, __ATOMIC_RELAXED, __HIP_MEMORY_SCOPE_AGENT)) < 32u) { __builtin_amdgcn_s_sleep(2); if (++sp > (1u << 21)) break; }
; __device__ __forceinline__ void fused_epi(f32x4 (&acc)[2][2][4][2], const Unit& u, int wr, int wc, int fr, int fq, LAS unsigned char* xl, int wid, int lane, const FuseArgs& f) {
;     ...
;                 for (int bj = 0; bj < 2; ++bj) { const size_t off = (size_t)(pm * BM + r) * DM + colb + bj * HALF;
;                     const u32x4 xw = *(const u32x4*)((const bf16_t*)(f.ws + WS_XR) + off);
.LBB0_271:
	s_or_b64 exec, exec, s[68:69]
	s_lshl_b32 s32, s53, 19
	s_add_u32 s34, s78, s32
	s_addc_u32 s35, s79, 0
	s_lshl_b32 s32, s16, 9
	s_add_u32 s34, s34, s32
	s_addc_u32 s35, s35, 0
	v_lshlrev_b32_e32 v217, 11, v167
	v_lshl_add_u32 v217, v191, 1, v217
	global_load_dwordx4 v[224:227], v217, s[34:35]
	global_load_dwordx4 v[228:231], v217, s[34:35] offset:256
	v_lshlrev_b32_e32 v217, 11, v176
	v_lshl_add_u32 v217, v191, 1, v217
	global_load_dwordx4 v[232:235], v217, s[34:35]
	global_load_dwordx4 v[236:239], v217, s[34:35] offset:256
	v_lshlrev_b32_e32 v217, 11, v178
	v_lshl_add_u32 v217, v191, 1, v217
	global_load_dwordx4 v[240:243], v217, s[34:35]
	global_load_dwordx4 v[244:247], v217, s[34:35] offset:256
	v_lshlrev_b32_e32 v217, 11, v180
	v_lshl_add_u32 v217, v191, 1, v217
	global_load_dwordx4 v[248:251], v217, s[34:35]
	v_readlane_b32 s26, v255, 21
	v_readlane_b32 s27, v255, 22
	s_andn2_b64 vcc, exec, s[26:27]
	s_cbranch_vccnz .LBB0_285
	s_lshl_b32 s62, s53, 6
	s_ashr_i32 s63, s62, 31
	s_lshl_b64 s[62:63], s[62:63], 2
	s_add_u32 s68, s41, s62
	s_addc_u32 s69, s47, s63
	s_mov_b32 s17, 0x200001
	s_branch .LBB0_274
